# v48 plus: v_max3 row-max tree in the peeled first attention tile (16 instead of 53 instructions)
# baseline (speedup 1.0000x reference)
.LBB0_202:
	s_nop 10
	v_max3_f32 v19, v0, v1, v2
	v_max3_f32 v20, v3, v4, v5
	v_max3_f32 v19, v19, v6, v7
	v_max3_f32 v20, v20, v8, v9
	v_max3_f32 v19, v19, v10, v11
	v_max3_f32 v20, v20, v12, v13
	v_max3_f32 v19, v19, v14, v15
	v_max3_f32 v20, v20, v64, v65
	v_max3_f32 v19, v19, v66, v67
	v_max3_f32 v20, v20, v68, v69
	v_max3_f32 v19, v19, v70, v71
	v_max3_f32 v20, v20, v72, v73
	v_max3_f32 v19, v19, v74, v75
	v_max3_f32 v20, v20, v76, v77
	v_cmp_lt_i32_e32 vcc, v234, v235
	v_max3_f32 v19, v19, v78, v79
	v_max_f32_e32 v19, v19, v20
	v_lshrrev_b32_e32 v17, 2, v87
	v_cndmask_b32_e32 v20, v233, v234, vcc
	v_lshlrev_b32_e32 v155, 2, v20
	ds_bpermute_b32 v20, v155, v19
	v_and_b32_e32 v18, 16, v87
	v_lshlrev_b32_e32 v21, 2, v87
	v_and_or_b32 v17, v17, 3, v151
	v_and_or_b32 v18, v21, 12, v18
	v_mul_u32_u24_e32 v17, 0x140, v17
	v_lshlrev_b32_e32 v18, 1, v18
	v_add3_u32 v160, 0, v17, v18
	s_waitcnt lgkmcnt(0)
	v_max_f32_e32 v17, v20, v20
	v_max_f32_e32 v80, v19, v17
	v_sub_f32_e32 v4, v4, v80
	v_sub_f32_e32 v5, v5, v80
	v_sub_f32_e32 v6, v6, v80
	v_sub_f32_e32 v7, v7, v80
	v_sub_f32_e32 v0, v0, v80
	v_sub_f32_e32 v1, v1, v80
	v_sub_f32_e32 v2, v2, v80
	v_sub_f32_e32 v3, v3, v80
	v_exp_f32_e32 v83, v4
	v_exp_f32_e32 v82, v5
	v_exp_f32_e32 v85, v6
	v_exp_f32_e32 v84, v7
	v_exp_f32_e32 v93, v0
	v_exp_f32_e32 v168, v1
	v_exp_f32_e32 v180, v2
	v_exp_f32_e32 v181, v3
	ds_read_b64_tr_b16 v[4:5], v160 offset:34816
	ds_read_b64_tr_b16 v[6:7], v160 offset:37376
	v_pk_mov_b32 v[2:3], v[82:83], v[82:83] op_sel:[1,0]
	v_pk_mov_b32 v[18:19], v[84:85], v[84:85] op_sel:[1,0]
	v_cvt_pk_bf16_f32 v0, v93, v168
	v_cvt_pk_bf16_f32 v1, v180, v181
	v_cvt_pk_bf16_f32 v2, v2, v3
	v_cvt_pk_bf16_f32 v3, v18, v19
	ds_read_b64_tr_b16 v[18:19], v160 offset:34880
	ds_read_b64_tr_b16 v[22:23], v160 offset:34944
	ds_read_b64_tr_b16 v[94:95], v160 offset:35008
	ds_read_b64_tr_b16 v[20:21], v160 offset:37440
	ds_read_b64_tr_b16 v[24:25], v160 offset:37504
	ds_read_b64_tr_b16 v[96:97], v160 offset:37568
	s_waitcnt lgkmcnt(6)
	v_mfma_f32_32x32x16_bf16 v[48:63], v[4:7], v[0:3], 0
	v_sub_f32_e32 v4, v8, v80
	v_sub_f32_e32 v5, v9, v80
	v_sub_f32_e32 v6, v10, v80
	v_sub_f32_e32 v7, v11, v80
	v_sub_f32_e32 v8, v12, v80
	v_sub_f32_e32 v9, v13, v80
	v_sub_f32_e32 v10, v14, v80
	v_sub_f32_e32 v11, v15, v80
	v_exp_f32_e32 v111, v4
	v_exp_f32_e32 v110, v5
	v_exp_f32_e32 v149, v6
	v_exp_f32_e32 v148, v7
	v_exp_f32_e32 v177, v8
	v_exp_f32_e32 v176, v9
	v_exp_f32_e32 v179, v10
	v_exp_f32_e32 v178, v11
	v_lshlrev_b32_e32 v182, 7, v16
	s_waitcnt lgkmcnt(2)
	v_mfma_f32_32x32x16_bf16 v[32:47], v[18:21], v[0:3], 0
	ds_read_b64_tr_b16 v[98:99], v160 offset:39936
	ds_read_b64_tr_b16 v[100:101], v160 offset:42496
	v_pk_mov_b32 v[102:103], v[178:179], v[178:179] op_sel:[1,0]
	v_sub_f32_e32 v68, v68, v80
	v_sub_f32_e32 v69, v69, v80
	v_sub_f32_e32 v70, v70, v80
	v_sub_f32_e32 v71, v71, v80
	v_lshlrev_b32_e32 v81, 1, v81
	s_waitcnt lgkmcnt(3)
	v_mfma_f32_32x32x16_bf16 v[16:31], v[22:25], v[0:3], 0
	v_sub_f32_e32 v64, v64, v80
	v_sub_f32_e32 v65, v65, v80
	v_sub_f32_e32 v66, v66, v80
	v_sub_f32_e32 v67, v67, v80
	v_add_u32_e32 v162, 2, v81
	v_exp_f32_e32 v81, v64
	v_exp_f32_e32 v183, v65
	s_waitcnt lgkmcnt(2)
	v_mfma_f32_32x32x16_bf16 v[0:15], v[94:97], v[0:3], 0
	v_pk_mov_b32 v[94:95], v[110:111], v[110:111] op_sel:[1,0]
	v_pk_mov_b32 v[96:97], v[148:149], v[148:149] op_sel:[1,0]
	v_cvt_pk_bf16_f32 v94, v94, v95
	v_cvt_pk_bf16_f32 v95, v96, v97
	v_pk_mov_b32 v[96:97], v[176:177], v[176:177] op_sel:[1,0]
	v_exp_f32_e32 v184, v66
	v_cvt_pk_bf16_f32 v96, v96, v97
	v_cvt_pk_bf16_f32 v97, v102, v103
	ds_read_b64_tr_b16 v[102:103], v160 offset:40000
	ds_read_b64_tr_b16 v[106:107], v160 offset:40064
	ds_read_b64_tr_b16 v[144:145], v160 offset:40128
	ds_read_b64_tr_b16 v[104:105], v160 offset:42560
	ds_read_b64_tr_b16 v[108:109], v160 offset:42624
	ds_read_b64_tr_b16 v[146:147], v160 offset:42688
	s_waitcnt lgkmcnt(6)
	v_mfma_f32_32x32x16_bf16 v[48:63], v[98:101], v[94:97], v[48:63]
	v_exp_f32_e32 v185, v67
	v_cvt_pk_bf16_f32 v64, v81, v183
	v_and_b32_e32 v161, 63, v87
	s_mov_b32 s26, 2
	v_cvt_pk_bf16_f32 v65, v184, v185
	v_lshrrev_b32_e32 v163, 6, v152
	s_mov_b32 s27, 0
	s_waitcnt lgkmcnt(1)
	v_mfma_f32_32x32x16_bf16 v[16:31], v[106:109], v[94:97], v[16:31]
	v_exp_f32_e32 v107, v68
	v_exp_f32_e32 v106, v69
	v_exp_f32_e32 v109, v70
	v_exp_f32_e32 v108, v71
	ds_read_b64_tr_b16 v[68:69], v160 offset:45056
	ds_read_b64_tr_b16 v[70:71], v160 offset:47616
	v_pk_mov_b32 v[66:67], v[106:107], v[106:107] op_sel:[1,0]
	v_mfma_f32_32x32x16_bf16 v[32:47], v[102:105], v[94:97], v[32:47]
	v_cvt_pk_bf16_f32 v66, v66, v67
	s_waitcnt lgkmcnt(2)
	v_mfma_f32_32x32x16_bf16 v[0:15], v[144:147], v[94:97], v[0:15]
	v_pk_mov_b32 v[94:95], v[108:109], v[108:109] op_sel:[1,0]
	s_nop 0
	v_cvt_pk_bf16_f32 v67, v94, v95
	ds_read_b64_tr_b16 v[94:95], v160 offset:45120
	ds_read_b64_tr_b16 v[98:99], v160 offset:45184
	ds_read_b64_tr_b16 v[102:103], v160 offset:45248
	ds_read_b64_tr_b16 v[96:97], v160 offset:47680
	ds_read_b64_tr_b16 v[100:101], v160 offset:47744
	ds_read_b64_tr_b16 v[104:105], v160 offset:47808
	s_waitcnt lgkmcnt(6)
	v_mfma_f32_32x32x16_bf16 v[48:63], v[68:71], v[64:67], v[48:63]
	v_sub_f32_e32 v68, v72, v80
	v_sub_f32_e32 v69, v73, v80
	v_sub_f32_e32 v70, v74, v80
	v_sub_f32_e32 v71, v75, v80
	v_sub_f32_e32 v72, v76, v80
	v_sub_f32_e32 v73, v77, v80
	v_sub_f32_e32 v74, v78, v80
	v_sub_f32_e32 v75, v79, v80
	v_exp_f32_e32 v145, v68
	s_waitcnt lgkmcnt(1)
	v_mfma_f32_32x32x16_bf16 v[16:31], v[98:101], v[64:67], v[16:31]
	v_exp_f32_e32 v144, v69
	v_exp_f32_e32 v99, v70
	v_exp_f32_e32 v98, v71
	v_exp_f32_e32 v101, v72
	v_exp_f32_e32 v100, v73
	v_exp_f32_e32 v147, v74
	v_exp_f32_e32 v146, v75
	ds_read_b64_tr_b16 v[68:69], v160 offset:50176
	ds_read_b64_tr_b16 v[70:71], v160 offset:52736
	v_mfma_f32_32x32x16_bf16 v[32:47], v[94:97], v[64:67], v[32:47]
	v_add_f32_e32 v76, v93, v81
	v_add_f32_e32 v76, 0, v76
	v_add_f32_e32 v77, v168, v183
	v_pk_mov_b32 v[72:73], v[146:147], v[146:147] op_sel:[1,0]
	v_add_f32_e32 v81, v77, v76
	v_add_f32_e32 v93, v180, v184
	s_waitcnt lgkmcnt(2)
	v_mfma_f32_32x32x16_bf16 v[0:15], v[102:105], v[64:67], v[0:15]
	v_pk_mov_b32 v[64:65], v[144:145], v[144:145] op_sel:[1,0]
	v_pk_mov_b32 v[66:67], v[98:99], v[98:99] op_sel:[1,0]
	v_cvt_pk_bf16_f32 v64, v64, v65
	v_cvt_pk_bf16_f32 v65, v66, v67
	v_pk_mov_b32 v[66:67], v[100:101], v[100:101] op_sel:[1,0]
	s_nop 0
	v_cvt_pk_bf16_f32 v66, v66, v67
	v_cvt_pk_bf16_f32 v67, v72, v73
	ds_read_b64_tr_b16 v[72:73], v160 offset:50240
	ds_read_b64_tr_b16 v[76:77], v160 offset:50304
	ds_read_b64_tr_b16 v[94:95], v160 offset:50368
	ds_read_b64_tr_b16 v[74:75], v160 offset:52800
	ds_read_b64_tr_b16 v[78:79], v160 offset:52864
	ds_read_b64_tr_b16 v[96:97], v160 offset:52928
	s_waitcnt lgkmcnt(6)
	v_mfma_f32_32x32x16_bf16 v[48:63], v[68:71], v[64:67], v[48:63]
	v_add_f32_e32 v68, v93, v81
	v_add_f32_e32 v69, v181, v185
	v_add_f32_e32 v70, v69, v68
	v_add_f32_e64 v68, v82, v106
	v_add_f32_e64 v69, v83, v107
	s_waitcnt vmcnt(3)
	ds_write_b128 v90, v[128:131] offset:17408
	s_waitcnt vmcnt(2)
	ds_write_b128 v92, v[132:135] offset:55296
	s_waitcnt vmcnt(1)
	ds_write_b128 v90, v[136:139] offset:26112
	s_waitcnt vmcnt(0)
	ds_write_b128 v91, v[140:143] offset:55296
	v_add_f32_e32 v69, v69, v70
	v_add_f32_e32 v70, v68, v69
	v_pk_add_f32 v[68:69], v[84:85], v[108:109]
	s_waitcnt lgkmcnt(6)
	v_mfma_f32_32x32x16_bf16 v[32:47], v[72:75], v[64:67], v[32:47]
	v_add_f32_e32 v69, v69, v70
	v_add_f32_e32 v70, v68, v69
	v_add_f32_e64 v68, v110, v144
	v_add_f32_e64 v69, v111, v145
	v_lshlrev_b32_e32 v144, 1, v182
	v_add_f32_e32 v69, v69, v70
	v_add_f32_e32 v70, v68, v69
	v_pk_add_f32 v[68:69], v[148:149], v[98:99]
	s_waitcnt lgkmcnt(5)
	v_mfma_f32_32x32x16_bf16 v[16:31], v[76:79], v[64:67], v[16:31]
	v_add_f32_e32 v69, v69, v70
	v_add_f32_e32 v70, v68, v69
	v_add_f32_e64 v68, v176, v100
	v_add_f32_e64 v69, v177, v101
	v_mov_b32_e32 v145, v169
	v_add_f32_e32 v69, v69, v70
	v_add_f32_e32 v70, v68, v69
	v_pk_add_f32 v[68:69], v[178:179], v[146:147]
	s_waitcnt lgkmcnt(4)
	v_mfma_f32_32x32x16_bf16 v[0:15], v[94:97], v[64:67], v[0:15]
	v_add_f32_e32 v69, v69, v70
	v_add_f32_e32 v81, v68, v69
	v_add_f32_e64 v146, v80, 0
	v_add_f32_e64 v147, v81, 0
	v_lshl_add_u64 v[68:69], s[16:17], 0, v[144:145]
	v_pk_add_f32 v[64:65], v[146:147], 0 neg_lo:[1,1] neg_hi:[1,1]
	v_add_u32_e32 v145, 64, v86
	v_add_u32_e32 v65, s28, v86
	v_add_u32_e32 v65, v65, v88
	v_sub_u32_e32 v176, v151, v65
	v_mad_i64_i32 v[66:67], s[28:29], v89, s10, 0
	v_and_b32_e32 v65, 15, v87
	v_lshl_or_b32 v66, v65, 4, v66
	v_lshl_add_u64 v[148:149], v[68:69], 0, v[66:67]
	v_mov_b32_e32 v65, v64
	v_mov_b32_e32 v66, v64
	v_mov_b32_e32 v67, v64
	v_mov_b32_e32 v68, v64
	v_mov_b32_e32 v69, v64
	v_mov_b32_e32 v70, v64
	v_mov_b32_e32 v71, v64
	v_mov_b32_e32 v72, v64
	v_mov_b32_e32 v73, v64
	v_mov_b32_e32 v74, v64
	v_mov_b32_e32 v75, v64
	v_mov_b32_e32 v76, v64
	v_mov_b32_e32 v77, v64
	v_mov_b32_e32 v78, v64
	v_mov_b32_e32 v79, v64
	s_waitcnt lgkmcnt(0)
	s_barrier
	s_branch .LBB0_204
